# HGRN2 pass 1: next unit's 48 operand loads prefetched into spare registers during the current unit's second half
# baseline (speedup 1.0000x reference)
; #define LAS __attribute__((address_space(3)))
; __device__ __forceinline__ void hgrn_pass1_unit(Frame& F, int unit) {
;     const int bh = unit >> 7, c = unit & 127, b = bh >> 2, h = bh & 3; const size_t row0 = (size_t)b * SEQ + c * 64;
;     float* LF = (float*)(F.ws + WS_LF); bf16* QO = (bf16*)(F.ws + WS_QO); const bf16* VH = (const bf16*)(F.ws + WS_VH);
;     bf16* UT = (bf16*)F.out + (size_t)unit * 16384; float* HD = (float*)(F.ws + WS_HD) + (size_t)unit * 128;
;     LAS bf16* Qm = (LAS bf16*)(F.lds + P1_QM); LAS bf16* Km = (LAS bf16*)(F.lds + P1_KM); LAS bf16* KlT = (LAS bf16*)(F.lds + P1_KLT); LAS bf16* VT = (LAS bf16*)(F.lds + P1_VT); LAS bf16* Am = (LAS bf16*)(F.lds + P1_AM);
;     LAS float* tot = (LAS float*)(F.lds + P1_TOT);
;     const int k = F.tid & 127, tq = F.tid >> 7, fr = F.lane & 15, fq = F.lane >> 4;
;     float lf[16], g[16]; unsigned short qv[16], vv[16];
; #pragma unroll
;     for (int i = 0; i < 16; ++i) { const size_t r = row0 + 16 * tq + i; lf[i] = LF[r * 512 + h * 128 + k]; qv[i] = QO[r * DM + h * 128 + k]; vv[i] = VH[r * 512 + h * 128 + k]; }
.LBB0_516:
	s_ashr_i32 s72, s2, 6
	s_add_u32 s89, s26, 0x3800000
	s_addc_u32 s90, s27, 0
	s_lshl_b32 s18, s72, 2
	v_lshlrev_b32_e32 v8, 4, v0
	s_add_i32 s91, s1, s18
	s_cmp_gt_i32 s72, 0
	v_ashrrev_i32_e32 v9, 31, v8
	v_and_b32_e32 v12, 0x7f, v0
	s_cselect_b64 s[50:51], -1, 0
	v_lshl_add_u64 v[2:3], v[8:9], 2, s[26:27]
	s_mov_b64 s[18:19], 0x3710000
	s_add_u32 s60, s26, 0x9a00000
	v_lshlrev_b32_e32 v192, 1, v12
	v_and_b32_e32 v1, 63, v0
	v_lshl_add_u64 v[10:11], v[2:3], 0, s[18:19]
	s_addc_u32 s61, s27, 0
	v_lshl_add_u64 v[2:3], s[26:27], 0, v[192:193]
	s_mov_b64 s[18:19], 0x5a00000
	v_cmp_eq_u32_e64 s[4:5], 0, v1
	v_cmp_gt_u32_e64 s[6:7], 2, v1
	v_cmp_gt_u32_e64 s[8:9], 4, v1
	v_cmp_gt_u32_e64 s[10:11], 8, v1
	v_cmp_gt_u32_e64 s[12:13], 16, v1
	v_cmp_gt_u32_e64 s[14:15], 32, v1
	v_cmp_eq_u32_e64 s[16:17], 63, v1
	s_add_u32 s64, s26, 0x7a00000
	v_ashrrev_i32_e32 v1, 7, v0
	v_lshl_add_u64 v[18:19], v[2:3], 0, s[18:19]
	v_mul_u32_u24_e32 v2, 0x48, v12
	s_addc_u32 s65, s27, 0
	s_add_i32 s18, s1, 0x13c00
	v_lshlrev_b32_e32 v2, 1, v2
	v_lshlrev_b32_e32 v3, 5, v1
	v_lshlrev_b32_e32 v192, 2, v12
	s_movk_i32 s24, 0x880
	v_lshlrev_b32_e32 v16, 4, v1
	v_lshl_add_u32 v9, v0, 2, s18
	v_add3_u32 v13, s1, v2, v3
	v_add_u32_e32 v15, s18, v192
	v_cmp_lt_i32_e64 s[18:19], 0, v1
	v_cmp_lt_i32_e64 s[20:21], 1, v1
	v_cmp_lt_i32_e64 s[22:23], 2, v1
	v_mul_lo_u32 v1, v1, s24
	v_lshl_add_u64 v[2:3], s[26:27], 0, v[192:193]
	s_mov_b64 s[26:27], 0x3900000
	s_add_i32 s28, s1, 0x11800
	v_or_b32_e32 v1, v1, v12
	v_lshl_add_u64 v[20:21], v[2:3], 0, s[26:27]
	s_ashr_i32 s2, s2, 8
	s_and_b32 s26, s72, 3
	v_lshl_add_u32 v23, v1, 1, s1
	v_lshrrev_b32_e32 v1, 2, v0
	s_cmp_le_i32 s2, s26
	v_and_b32_e32 v14, 15, v0
	s_movk_i32 s24, 0x80
	v_and_b32_e32 v2, 12, v1
	s_cselect_b64 s[66:67], -1, 0
	s_lshl_b32 s2, s2, 4
	v_cmp_gt_u32_e64 s[24:25], s24, v0
	v_and_b32_e32 v1, 48, v0
	v_or_b32_e32 v0, s2, v14
	v_or_b32_e32 v27, s2, v2
	s_add_i32 s2, s72, 8
	s_ashr_i32 s2, s2, 2
	s_cmp_le_i32 s2, s26
	s_movk_i32 s27, 0x110
	s_cselect_b64 s[70:71], -1, 0
	s_lshl_b32 s2, s2, 4
	v_mul_lo_u32 v3, v0, s27
	v_or_b32_e32 v0, s2, v14
	s_lshl_b32 s78, s72, 4
	v_add_u32_e32 v22, s1, v1
	v_mul_lo_u32 v33, v0, s27
	v_or_b32_e32 v34, s2, v2
	v_or_b32_e32 v0, s78, v14
	s_movk_i32 s2, 0x90
	v_lshl_or_b32 v5, s26, 4, v14
	v_mad_u64_u32 v[24:25], s[26:27], v0, s2, v[22:23]
	v_lshlrev_b32_e32 v0, 7, v14
	s_ashr_i32 s79, s78, 31
	v_or_b32_e32 v26, 16, v14
	v_mov_b32_e32 v4, 0x900
	v_or_b32_e32 v28, 32, v14
	v_mov_b32_e32 v6, 0x1200
	v_or_b32_e32 v30, 48, v14
	v_mul_u32_u24_e32 v7, 0x110, v5
	v_or_b32_e32 v29, 2, v27
	v_or_b32_e32 v31, 3, v27
	v_lshl_add_u32 v32, v27, 1, s28
	v_or_b32_e32 v35, 2, v34
	v_or_b32_e32 v36, 3, v34
	v_lshl_add_u32 v37, v34, 1, s28
	v_mul_u32_u24_e32 v25, 0x90, v14
	v_mad_u32_u24 v39, v14, s2, v4
	v_lshlrev_b32_e32 v4, 7, v26
	v_mad_u32_u24 v41, v14, s2, v6
	v_lshlrev_b32_e32 v6, 7, v28
	v_lshlrev_b32_e32 v38, 7, v30
	v_or_b32_e32 v40, 0x2000, v0
	v_or_b32_e32 v42, 0x2800, v0
	v_or_b32_e32 v44, 0x3000, v0
	v_or_b32_e32 v46, 0x3800, v0
	v_add_u32_e32 v1, s28, v1
	s_add_u32 s74, s48, 0x2000000
	v_mul_u32_u24_e32 v43, 0x90, v5
	v_ashrrev_i32_e32 v17, 31, v16
	s_addc_u32 s75, s49, 0
	v_cmp_gt_i32_e64 s[26:27], v27, v5
	v_cmp_lt_i32_e64 s[28:29], v27, v5
	v_cmp_gt_i32_e64 s[30:31], v29, v5
	v_cmp_gt_i32_e64 s[34:35], v31, v5
	v_cmp_gt_i32_e64 s[36:37], v34, v5
	v_cmp_lt_i32_e64 s[38:39], v34, v5
	v_cmp_gt_i32_e64 s[40:41], v35, v5
	v_cmp_gt_i32_e64 s[42:43], v36, v5
	v_add_u32_e32 v27, v22, v3
	v_add_u32_e32 v29, v32, v43
	v_add_u32_e32 v31, v22, v33
	v_add_u32_e32 v78, v37, v43
	v_lshlrev_b32_e32 v192, 1, v0
	s_lshl_b64 s[78:79], s[78:79], 1
	v_lshlrev_b32_e32 v32, 1, v2
	v_lshlrev_b32_e32 v34, 1, v4
	v_lshlrev_b32_e32 v36, 1, v6
	v_lshlrev_b32_e32 v38, 1, v38
	v_lshlrev_b32_e32 v40, 1, v40
	v_lshlrev_b32_e32 v42, 1, v42
	v_add_u32_e32 v79, v22, v39
	v_lshlrev_b32_e32 v44, 1, v44
	v_add_u32_e32 v80, v22, v41
	v_lshlrev_b32_e32 v46, 1, v46
	v_add_u32_e32 v81, v1, v25
	v_add_u32_e32 v82, v22, v7
	s_mov_b32 vcc_lo, s44
	s_cmpk_gt_i32 vcc_lo, 0x3ff
	s_cbranch_scc1 .Lp1pf_a
	v_mov_b32_e32 v245, vcc_lo
	v_lshrrev_b32_e32 v236, 9, v245
	v_lshlrev_b32_e32 v236, 13, v236
	v_lshlrev_b32_e32 v237, 6, v245
	v_and_b32_e32 v237, 0x1fc0, v237
	v_or_b32_e32 v236, v236, v237
	v_mov_b32_e32 v237, 0
	v_and_b32_e32 v235, 0x180, v245
	v_lshlrev_b32_e32 v240, 1, v235
	v_mov_b32_e32 v241, s69
	v_lshl_add_u64 v[138:139], v[236:237], 0, v[16:17]
	v_lshlrev_b64 v[140:141], 9, v[138:139]
	v_or_b32_e32 v140, v140, v12
	v_or_b32_e32 v140, v235, v140
	v_lshl_add_u64 v[142:143], v[140:141], 2, s[60:61]
	v_lshl_add_u64 v[140:141], v[140:141], 1, s[64:65]
	v_lshl_add_u64 v[170:171], v[18:19], 0, v[240:241]
	global_load_dword v226, v[142:143], off
	global_load_ushort v172, v[140:141], off
	v_lshlrev_b64 v[142:143], 11, v[138:139]
	v_or_b32_e32 v140, 1, v138
	v_mov_b32_e32 v141, v139
	v_lshl_add_u64 v[168:169], v[170:171], 0, v[142:143]
	v_lshlrev_b64 v[142:143], 9, v[140:141]
	v_or_b32_e32 v142, v142, v12
	v_or_b32_e32 v142, v235, v142
	v_lshlrev_b64 v[140:141], 11, v[140:141]
	v_lshl_add_u64 v[144:145], v[142:143], 2, s[60:61]
	v_lshl_add_u64 v[164:165], v[170:171], 0, v[140:141]
	v_lshl_add_u64 v[140:141], v[142:143], 1, s[64:65]
	global_load_dword v179, v[144:145], off
	global_load_ushort v173, v[140:141], off
	v_or_b32_e32 v140, 2, v138
	v_mov_b32_e32 v141, v139
	v_lshlrev_b64 v[142:143], 9, v[140:141]
	v_or_b32_e32 v142, v142, v12
	v_or_b32_e32 v142, v235, v142
	v_lshlrev_b64 v[140:141], 11, v[140:141]
	v_lshl_add_u64 v[144:145], v[142:143], 2, s[60:61]
	v_lshl_add_u64 v[166:167], v[170:171], 0, v[140:141]
; __device__ __forceinline__ void hgrn_pass1_unit(Frame& F, int unit) {
;     ...
; #pragma unroll
;     for (int i = 0; i < 16; ++i) { const size_t r = row0 + 16 * tq + i; lf[i] = LF[r * 512 + h * 128 + k]; qv[i] = QO[r * DM + h * 128 + k]; vv[i] = VH[r * 512 + h * 128 + k]; }
	v_lshl_add_u64 v[140:141], v[142:143], 1, s[64:65]
	global_load_dword v178, v[144:145], off
	global_load_ushort v174, v[140:141], off
	v_or_b32_e32 v140, 3, v138
	v_mov_b32_e32 v141, v139
	v_lshlrev_b64 v[142:143], 9, v[140:141]
	v_or_b32_e32 v142, v142, v12
	v_or_b32_e32 v142, v235, v142
	v_lshlrev_b64 v[140:141], 11, v[140:141]
	v_lshl_add_u64 v[144:145], v[142:143], 2, s[60:61]
	v_lshl_add_u64 v[160:161], v[170:171], 0, v[140:141]
	v_lshl_add_u64 v[140:141], v[142:143], 1, s[64:65]
	global_load_dword v225, v[144:145], off
	global_load_ushort v175, v[140:141], off
	v_or_b32_e32 v140, 4, v138
	v_mov_b32_e32 v141, v139
	v_lshlrev_b64 v[142:143], 9, v[140:141]
	v_or_b32_e32 v142, v142, v12
	v_or_b32_e32 v142, v235, v142
	v_lshlrev_b64 v[140:141], 11, v[140:141]
	v_lshl_add_u64 v[144:145], v[142:143], 2, s[60:61]
	v_lshl_add_u64 v[162:163], v[170:171], 0, v[140:141]
	v_lshl_add_u64 v[140:141], v[142:143], 1, s[64:65]
	global_load_dword v177, v[144:145], off
	global_load_ushort v185, v[140:141], off
	v_or_b32_e32 v140, 5, v138
	v_mov_b32_e32 v141, v139
	v_lshlrev_b64 v[142:143], 9, v[140:141]
	v_or_b32_e32 v142, v142, v12
	v_or_b32_e32 v142, v235, v142
	v_lshlrev_b64 v[140:141], 11, v[140:141]
	v_lshl_add_u64 v[144:145], v[142:143], 2, s[60:61]
	v_lshl_add_u64 v[156:157], v[170:171], 0, v[140:141]
	v_lshl_add_u64 v[140:141], v[142:143], 1, s[64:65]
	global_load_dword v176, v[144:145], off
	global_load_ushort v228, v[140:141], off
	v_or_b32_e32 v140, 6, v138
	v_mov_b32_e32 v141, v139
	v_lshlrev_b64 v[142:143], 9, v[140:141]
	v_or_b32_e32 v142, v142, v12
	v_or_b32_e32 v142, v235, v142
	v_lshlrev_b64 v[140:141], 11, v[140:141]
	v_lshl_add_u64 v[144:145], v[142:143], 2, s[60:61]
	v_lshl_add_u64 v[158:159], v[170:171], 0, v[140:141]
	v_lshl_add_u64 v[140:141], v[142:143], 1, s[64:65]
	global_load_dword v224, v[144:145], off
	global_load_ushort v187, v[140:141], off
	v_or_b32_e32 v140, 7, v138
	v_mov_b32_e32 v141, v139
	v_lshlrev_b64 v[142:143], 9, v[140:141]
	v_or_b32_e32 v142, v142, v12
	v_or_b32_e32 v142, v235, v142
	v_lshlrev_b64 v[140:141], 11, v[140:141]
	v_lshl_add_u64 v[144:145], v[142:143], 2, s[60:61]
	v_lshl_add_u64 v[152:153], v[170:171], 0, v[140:141]
	v_lshl_add_u64 v[140:141], v[142:143], 1, s[64:65]
	global_load_dword v223, v[144:145], off
	global_load_ushort v188, v[140:141], off
	v_or_b32_e32 v140, 8, v138
	v_mov_b32_e32 v141, v139
	v_lshlrev_b64 v[142:143], 9, v[140:141]
	v_or_b32_e32 v142, v142, v12
	v_or_b32_e32 v142, v235, v142
	v_lshlrev_b64 v[140:141], 11, v[140:141]
	v_lshl_add_u64 v[144:145], v[142:143], 2, s[60:61]
	v_lshl_add_u64 v[154:155], v[170:171], 0, v[140:141]
	v_lshl_add_u64 v[140:141], v[142:143], 1, s[64:65]
	global_load_dword v222, v[144:145], off
	global_load_ushort v229, v[140:141], off
	v_or_b32_e32 v140, 9, v138
	v_mov_b32_e32 v141, v139
	v_lshlrev_b64 v[142:143], 9, v[140:141]
	v_or_b32_e32 v142, v142, v12
	v_or_b32_e32 v142, v235, v142
	v_lshlrev_b64 v[140:141], 11, v[140:141]
	v_lshl_add_u64 v[144:145], v[142:143], 2, s[60:61]
	v_lshl_add_u64 v[148:149], v[170:171], 0, v[140:141]
	v_lshl_add_u64 v[140:141], v[142:143], 1, s[64:65]
	global_load_dword v221, v[144:145], off
	global_load_ushort v190, v[140:141], off
	v_or_b32_e32 v140, 10, v138
	v_mov_b32_e32 v141, v139
	v_lshlrev_b64 v[142:143], 9, v[140:141]
	v_or_b32_e32 v142, v142, v12
	v_or_b32_e32 v142, v235, v142
	v_lshlrev_b64 v[140:141], 11, v[140:141]
	v_lshl_add_u64 v[144:145], v[142:143], 2, s[60:61]
	v_lshl_add_u64 v[150:151], v[170:171], 0, v[140:141]
	v_lshl_add_u64 v[140:141], v[142:143], 1, s[64:65]
	global_load_dword v220, v[144:145], off
	global_load_ushort v230, v[140:141], off
	v_or_b32_e32 v140, 11, v138
	v_mov_b32_e32 v141, v139
	v_lshlrev_b64 v[142:143], 9, v[140:141]
	v_or_b32_e32 v142, v142, v12
	v_or_b32_e32 v142, v235, v142
	v_lshl_add_u64 v[144:145], v[142:143], 2, s[60:61]
	v_lshlrev_b64 v[140:141], 11, v[140:141]
	global_load_dword v219, v[144:145], off
	v_lshl_add_u64 v[144:145], v[170:171], 0, v[140:141]
	v_lshl_add_u64 v[140:141], v[142:143], 1, s[64:65]
	global_load_ushort v195, v[140:141], off
	v_or_b32_e32 v140, 12, v138
	v_mov_b32_e32 v141, v139
	v_lshlrev_b64 v[142:143], 9, v[140:141]
	v_or_b32_e32 v142, v142, v12
	v_or_b32_e32 v142, v235, v142
	v_lshl_add_u64 v[146:147], v[142:143], 2, s[60:61]
	v_lshlrev_b64 v[140:141], 11, v[140:141]
	global_load_dword v218, v[146:147], off
	v_lshl_add_u64 v[146:147], v[170:171], 0, v[140:141]
	v_lshl_add_u64 v[140:141], v[142:143], 1, s[64:65]
	global_load_ushort v232, v[140:141], off
	v_or_b32_e32 v140, 13, v138
	v_mov_b32_e32 v141, v139
	v_lshlrev_b64 v[142:143], 9, v[140:141]
	v_or_b32_e32 v142, v142, v12
	v_or_b32_e32 v142, v235, v142
	v_lshl_add_u64 v[180:181], v[142:143], 2, s[60:61]
	v_lshl_add_u64 v[142:143], v[142:143], 1, s[64:65]
	global_load_dword v214, v[180:181], off
	global_load_ushort v204, v[142:143], off
	v_or_b32_e32 v142, 14, v138
	v_mov_b32_e32 v143, v139
	v_lshlrev_b64 v[180:181], 9, v[142:143]
	v_or_b32_e32 v137, v180, v12
	v_or_b32_e32 v180, v235, v137
	v_lshl_add_u64 v[182:183], v[180:181], 2, s[60:61]
	v_lshl_add_u64 v[180:181], v[180:181], 1, s[64:65]
	v_or_b32_e32 v138, 15, v138
	global_load_ushort v205, v[180:181], off
	v_lshlrev_b64 v[180:181], 9, v[138:139]
	v_or_b32_e32 v137, v180, v12
	v_lshlrev_b64 v[140:141], 11, v[140:141]
	v_lshlrev_b64 v[142:143], 11, v[142:143]
	v_or_b32_e32 v180, v235, v137
	v_lshlrev_b64 v[138:139], 11, v[138:139]
	v_lshl_add_u64 v[140:141], v[170:171], 0, v[140:141]
	v_lshl_add_u64 v[142:143], v[170:171], 0, v[142:143]
	v_lshl_add_u64 v[138:139], v[170:171], 0, v[138:139]
	v_lshl_add_u64 v[170:171], v[180:181], 1, s[64:65]
	global_load_dword v202, v[182:183], off
	global_load_ushort v170, v[170:171], off
	v_lshl_add_u64 v[182:183], v[180:181], 2, s[60:61]
	global_load_dword v137, v[182:183], off
	global_load_ushort v233, v[168:169], off
	global_load_ushort v206, v[164:165], off
	global_load_ushort v207, v[166:167], off
	global_load_ushort v208, v[160:161], off
	global_load_ushort v209, v[162:163], off
	global_load_ushort v210, v[156:157], off
	global_load_ushort v211, v[158:159], off
	global_load_ushort v234, v[152:153], off
	global_load_ushort v231, v[154:155], off
	global_load_ushort v194, v[148:149], off
	global_load_ushort v191, v[150:151], off
	global_load_ushort v189, v[144:145], off
	global_load_ushort v186, v[146:147], off
	global_load_ushort v227, v[140:141], off
	global_load_ushort v184, v[142:143], off
	global_load_ushort v182, v[138:139], off

; __device__ __forceinline__ void hgrn_pass1_unit(Frame& F, int unit) {
;     ...
; #pragma unroll
;     for (int i = 0; i < 16; ++i) { const size_t r = row0 + 16 * tq + i; lf[i] = LF[r * 512 + h * 128 + k]; qv[i] = QO[r * DM + h * 128 + k]; vv[i] = VH[r * 512 + h * 128 + k]; }
.LBB0_517:
	s_add_i32 vcc_lo, s44, s0
	s_cmpk_gt_i32 vcc_lo, 0x3ff
	s_cbranch_scc1 .Lp1pf_b
	v_mov_b32_e32 v245, vcc_lo
	v_lshrrev_b32_e32 v236, 9, v245
	v_lshlrev_b32_e32 v236, 13, v236
	v_lshlrev_b32_e32 v237, 6, v245
	v_and_b32_e32 v237, 0x1fc0, v237
	v_or_b32_e32 v236, v236, v237
	v_mov_b32_e32 v237, 0
	v_and_b32_e32 v235, 0x180, v245
	v_lshlrev_b32_e32 v240, 1, v235
	v_mov_b32_e32 v241, s69
	v_lshl_add_u64 v[138:139], v[236:237], 0, v[16:17]
	v_lshlrev_b64 v[140:141], 9, v[138:139]
	v_or_b32_e32 v140, v140, v12
	v_or_b32_e32 v140, v235, v140
	v_lshl_add_u64 v[142:143], v[140:141], 2, s[60:61]
	v_lshl_add_u64 v[140:141], v[140:141], 1, s[64:65]
	v_lshl_add_u64 v[170:171], v[18:19], 0, v[240:241]
	global_load_dword v226, v[142:143], off
	global_load_ushort v172, v[140:141], off
	v_lshlrev_b64 v[142:143], 11, v[138:139]
	v_or_b32_e32 v140, 1, v138
	v_mov_b32_e32 v141, v139
	v_lshl_add_u64 v[168:169], v[170:171], 0, v[142:143]
	v_lshlrev_b64 v[142:143], 9, v[140:141]
	v_or_b32_e32 v142, v142, v12
	v_or_b32_e32 v142, v235, v142
	v_lshlrev_b64 v[140:141], 11, v[140:141]
	v_lshl_add_u64 v[144:145], v[142:143], 2, s[60:61]
	v_lshl_add_u64 v[164:165], v[170:171], 0, v[140:141]
	v_lshl_add_u64 v[140:141], v[142:143], 1, s[64:65]
	global_load_dword v179, v[144:145], off
	global_load_ushort v173, v[140:141], off
	v_or_b32_e32 v140, 2, v138
	v_mov_b32_e32 v141, v139
	v_lshlrev_b64 v[142:143], 9, v[140:141]
	v_or_b32_e32 v142, v142, v12
	v_or_b32_e32 v142, v235, v142
	v_lshlrev_b64 v[140:141], 11, v[140:141]
	v_lshl_add_u64 v[144:145], v[142:143], 2, s[60:61]
	v_lshl_add_u64 v[166:167], v[170:171], 0, v[140:141]
	v_lshl_add_u64 v[140:141], v[142:143], 1, s[64:65]
	global_load_dword v178, v[144:145], off
	global_load_ushort v174, v[140:141], off
	v_or_b32_e32 v140, 3, v138
	v_mov_b32_e32 v141, v139
	v_lshlrev_b64 v[142:143], 9, v[140:141]
	v_or_b32_e32 v142, v142, v12
	v_or_b32_e32 v142, v235, v142
	v_lshlrev_b64 v[140:141], 11, v[140:141]
	v_lshl_add_u64 v[144:145], v[142:143], 2, s[60:61]
	v_lshl_add_u64 v[160:161], v[170:171], 0, v[140:141]
	v_lshl_add_u64 v[140:141], v[142:143], 1, s[64:65]
	global_load_dword v225, v[144:145], off
	global_load_ushort v175, v[140:141], off
	v_or_b32_e32 v140, 4, v138
	v_mov_b32_e32 v141, v139
	v_lshlrev_b64 v[142:143], 9, v[140:141]
	v_or_b32_e32 v142, v142, v12
	v_or_b32_e32 v142, v235, v142
	v_lshlrev_b64 v[140:141], 11, v[140:141]
	v_lshl_add_u64 v[144:145], v[142:143], 2, s[60:61]
	v_lshl_add_u64 v[162:163], v[170:171], 0, v[140:141]
	v_lshl_add_u64 v[140:141], v[142:143], 1, s[64:65]
	global_load_dword v177, v[144:145], off
	global_load_ushort v185, v[140:141], off
	v_or_b32_e32 v140, 5, v138
	v_mov_b32_e32 v141, v139
	v_lshlrev_b64 v[142:143], 9, v[140:141]
	v_or_b32_e32 v142, v142, v12
	v_or_b32_e32 v142, v235, v142
	v_lshlrev_b64 v[140:141], 11, v[140:141]
	v_lshl_add_u64 v[144:145], v[142:143], 2, s[60:61]
	v_lshl_add_u64 v[156:157], v[170:171], 0, v[140:141]
	v_lshl_add_u64 v[140:141], v[142:143], 1, s[64:65]
	global_load_dword v176, v[144:145], off
	global_load_ushort v228, v[140:141], off
	v_or_b32_e32 v140, 6, v138
	v_mov_b32_e32 v141, v139
	v_lshlrev_b64 v[142:143], 9, v[140:141]
	v_or_b32_e32 v142, v142, v12
	v_or_b32_e32 v142, v235, v142
	v_lshlrev_b64 v[140:141], 11, v[140:141]
	v_lshl_add_u64 v[144:145], v[142:143], 2, s[60:61]
	v_lshl_add_u64 v[158:159], v[170:171], 0, v[140:141]
	v_lshl_add_u64 v[140:141], v[142:143], 1, s[64:65]
	global_load_dword v224, v[144:145], off
	global_load_ushort v187, v[140:141], off
	v_or_b32_e32 v140, 7, v138
	v_mov_b32_e32 v141, v139
	v_lshlrev_b64 v[142:143], 9, v[140:141]
	v_or_b32_e32 v142, v142, v12
	v_or_b32_e32 v142, v235, v142
	v_lshlrev_b64 v[140:141], 11, v[140:141]
	v_lshl_add_u64 v[144:145], v[142:143], 2, s[60:61]
	v_lshl_add_u64 v[152:153], v[170:171], 0, v[140:141]
	v_lshl_add_u64 v[140:141], v[142:143], 1, s[64:65]
	global_load_dword v223, v[144:145], off
	global_load_ushort v188, v[140:141], off
	v_or_b32_e32 v140, 8, v138
	v_mov_b32_e32 v141, v139
	v_lshlrev_b64 v[142:143], 9, v[140:141]
; __device__ __forceinline__ void hgrn_pass1_unit(Frame& F, int unit) {
;     ...
; #pragma unroll
;     for (int i = 0; i < 16; ++i) { const size_t r = row0 + 16 * tq + i; lf[i] = LF[r * 512 + h * 128 + k]; qv[i] = QO[r * DM + h * 128 + k]; vv[i] = VH[r * 512 + h * 128 + k]; }
	v_or_b32_e32 v142, v142, v12
	v_or_b32_e32 v142, v235, v142
	v_lshlrev_b64 v[140:141], 11, v[140:141]
	v_lshl_add_u64 v[144:145], v[142:143], 2, s[60:61]
	v_lshl_add_u64 v[154:155], v[170:171], 0, v[140:141]
	v_lshl_add_u64 v[140:141], v[142:143], 1, s[64:65]
	global_load_dword v222, v[144:145], off
	global_load_ushort v229, v[140:141], off
	v_or_b32_e32 v140, 9, v138
	v_mov_b32_e32 v141, v139
	v_lshlrev_b64 v[142:143], 9, v[140:141]
	v_or_b32_e32 v142, v142, v12
	v_or_b32_e32 v142, v235, v142
	v_lshlrev_b64 v[140:141], 11, v[140:141]
	v_lshl_add_u64 v[144:145], v[142:143], 2, s[60:61]
	v_lshl_add_u64 v[148:149], v[170:171], 0, v[140:141]
	v_lshl_add_u64 v[140:141], v[142:143], 1, s[64:65]
	global_load_dword v221, v[144:145], off
	global_load_ushort v190, v[140:141], off
	v_or_b32_e32 v140, 10, v138
	v_mov_b32_e32 v141, v139
	v_lshlrev_b64 v[142:143], 9, v[140:141]
	v_or_b32_e32 v142, v142, v12
	v_or_b32_e32 v142, v235, v142
	v_lshlrev_b64 v[140:141], 11, v[140:141]
	v_lshl_add_u64 v[144:145], v[142:143], 2, s[60:61]
	v_lshl_add_u64 v[150:151], v[170:171], 0, v[140:141]
	v_lshl_add_u64 v[140:141], v[142:143], 1, s[64:65]
	global_load_dword v220, v[144:145], off
	global_load_ushort v230, v[140:141], off
	v_or_b32_e32 v140, 11, v138
	v_mov_b32_e32 v141, v139
	v_lshlrev_b64 v[142:143], 9, v[140:141]
	v_or_b32_e32 v142, v142, v12
	v_or_b32_e32 v142, v235, v142
	v_lshl_add_u64 v[144:145], v[142:143], 2, s[60:61]
	v_lshlrev_b64 v[140:141], 11, v[140:141]
	global_load_dword v219, v[144:145], off
	v_lshl_add_u64 v[144:145], v[170:171], 0, v[140:141]
	v_lshl_add_u64 v[140:141], v[142:143], 1, s[64:65]
	global_load_ushort v195, v[140:141], off
	v_or_b32_e32 v140, 12, v138
	v_mov_b32_e32 v141, v139
	v_lshlrev_b64 v[142:143], 9, v[140:141]
	v_or_b32_e32 v142, v142, v12
	v_or_b32_e32 v142, v235, v142
	v_lshl_add_u64 v[146:147], v[142:143], 2, s[60:61]
	v_lshlrev_b64 v[140:141], 11, v[140:141]
	global_load_dword v218, v[146:147], off
	v_lshl_add_u64 v[146:147], v[170:171], 0, v[140:141]
	v_lshl_add_u64 v[140:141], v[142:143], 1, s[64:65]
	global_load_ushort v232, v[140:141], off
	v_or_b32_e32 v140, 13, v138
	v_mov_b32_e32 v141, v139
	v_lshlrev_b64 v[142:143], 9, v[140:141]
	v_or_b32_e32 v142, v142, v12
	v_or_b32_e32 v142, v235, v142
	v_lshl_add_u64 v[180:181], v[142:143], 2, s[60:61]
	v_lshl_add_u64 v[142:143], v[142:143], 1, s[64:65]
	global_load_dword v214, v[180:181], off
	global_load_ushort v204, v[142:143], off
	v_or_b32_e32 v142, 14, v138
	v_mov_b32_e32 v143, v139
	v_lshlrev_b64 v[180:181], 9, v[142:143]
	v_or_b32_e32 v137, v180, v12
	v_or_b32_e32 v180, v235, v137
	v_lshl_add_u64 v[182:183], v[180:181], 2, s[60:61]
	v_lshl_add_u64 v[180:181], v[180:181], 1, s[64:65]
	v_or_b32_e32 v138, 15, v138
	global_load_ushort v205, v[180:181], off
	v_lshlrev_b64 v[180:181], 9, v[138:139]
	v_or_b32_e32 v137, v180, v12
	v_lshlrev_b64 v[140:141], 11, v[140:141]
	v_lshlrev_b64 v[142:143], 11, v[142:143]
	v_or_b32_e32 v180, v235, v137
	v_lshlrev_b64 v[138:139], 11, v[138:139]
	v_lshl_add_u64 v[140:141], v[170:171], 0, v[140:141]
	v_lshl_add_u64 v[142:143], v[170:171], 0, v[142:143]
	v_lshl_add_u64 v[138:139], v[170:171], 0, v[138:139]
	v_lshl_add_u64 v[170:171], v[180:181], 1, s[64:65]
	global_load_dword v202, v[182:183], off
	global_load_ushort v170, v[170:171], off
	v_lshl_add_u64 v[182:183], v[180:181], 2, s[60:61]
	global_load_dword v137, v[182:183], off
	global_load_ushort v233, v[168:169], off
	global_load_ushort v206, v[164:165], off
	global_load_ushort v207, v[166:167], off
	global_load_ushort v208, v[160:161], off
	global_load_ushort v209, v[162:163], off
	global_load_ushort v210, v[156:157], off
	global_load_ushort v211, v[158:159], off
	global_load_ushort v234, v[152:153], off
	global_load_ushort v231, v[154:155], off
	global_load_ushort v194, v[148:149], off
	global_load_ushort v191, v[150:151], off
	global_load_ushort v189, v[144:145], off
	global_load_ushort v186, v[146:147], off
	global_load_ushort v227, v[140:141], off
	global_load_ushort v184, v[142:143], off
	global_load_ushort v182, v[138:139], off

; #define LAS __attribute__((address_space(3)))
; __device__ __forceinline__ void hgrn_pass1_unit(Frame& F, int unit) {
;     const int bh = unit >> 7, c = unit & 127, b = bh >> 2, h = bh & 3; const size_t row0 = (size_t)b * SEQ + c * 64;
;     float* LF = (float*)(F.ws + WS_LF); bf16* QO = (bf16*)(F.ws + WS_QO); const bf16* VH = (const bf16*)(F.ws + WS_VH);
;     bf16* UT = (bf16*)F.out + (size_t)unit * 16384; float* HD = (float*)(F.ws + WS_HD) + (size_t)unit * 128;
;     LAS bf16* Qm = (LAS bf16*)(F.lds + P1_QM); LAS bf16* Km = (LAS bf16*)(F.lds + P1_KM); LAS bf16* KlT = (LAS bf16*)(F.lds + P1_KLT); LAS bf16* VT = (LAS bf16*)(F.lds + P1_VT); LAS bf16* Am = (LAS bf16*)(F.lds + P1_AM);
;     LAS float* tot = (LAS float*)(F.lds + P1_TOT);
;     const int k = F.tid & 127, tq = F.tid >> 7, fr = F.lane & 15, fq = F.lane >> 4;
;     float lf[16], g[16]; unsigned short qv[16], vv[16];
; #pragma unroll
;     for (int i = 0; i < 16; ++i) { const size_t r = row0 + 16 * tq + i; lf[i] = LF[r * 512 + h * 128 + k]; qv[i] = QO[r * DM + h * 128 + k]; vv[i] = VH[r * 512 + h * 128 + k]; }
.LBB0_526:
	s_ashr_i32 s82, s44, 9
	s_ashr_i32 s83, s82, 31
	s_lshl_b32 s2, s44, 6
	s_lshl_b64 s[82:83], s[82:83], 13
	s_and_b32 s2, s2, 0x1fc0
	s_or_b32 s82, s82, s2
	v_lshl_add_u64 v[0:1], s[82:83], 0, v[16:17]
	v_lshlrev_b64 v[2:3], 9, v[0:1]
	s_and_b32 s84, s44, 0x180
	v_or_b32_e32 v2, v2, v12
	v_or_b32_e32 v2, s84, v2
	s_lshl_b32 s68, s84, 1
	v_lshl_add_u64 v[4:5], v[2:3], 2, s[60:61]
	v_lshl_add_u64 v[2:3], v[2:3], 1, s[64:65]
	v_lshl_add_u64 v[72:73], v[18:19], 0, s[68:69]
	v_lshlrev_b64 v[4:5], 11, v[0:1]
	v_or_b32_e32 v2, 1, v0
	v_mov_b32_e32 v3, v1
	v_lshl_add_u64 v[70:71], v[72:73], 0, v[4:5]
	v_lshlrev_b64 v[4:5], 9, v[2:3]
	v_or_b32_e32 v4, v4, v12
	v_or_b32_e32 v4, s84, v4
	v_lshlrev_b64 v[2:3], 11, v[2:3]
	v_lshl_add_u64 v[6:7], v[4:5], 2, s[60:61]
	v_lshl_add_u64 v[66:67], v[72:73], 0, v[2:3]
	v_lshl_add_u64 v[2:3], v[4:5], 1, s[64:65]
	v_or_b32_e32 v2, 2, v0
	v_mov_b32_e32 v3, v1
	v_lshlrev_b64 v[4:5], 9, v[2:3]
	v_or_b32_e32 v4, v4, v12
	v_or_b32_e32 v4, s84, v4
	v_lshlrev_b64 v[2:3], 11, v[2:3]
	v_lshl_add_u64 v[6:7], v[4:5], 2, s[60:61]
	v_lshl_add_u64 v[68:69], v[72:73], 0, v[2:3]
	v_lshl_add_u64 v[2:3], v[4:5], 1, s[64:65]
	v_or_b32_e32 v2, 3, v0
	v_mov_b32_e32 v3, v1
	v_lshlrev_b64 v[4:5], 9, v[2:3]
	v_or_b32_e32 v4, v4, v12
	v_or_b32_e32 v4, s84, v4
	v_lshlrev_b64 v[2:3], 11, v[2:3]
	v_lshl_add_u64 v[6:7], v[4:5], 2, s[60:61]
	v_lshl_add_u64 v[62:63], v[72:73], 0, v[2:3]
	v_lshl_add_u64 v[2:3], v[4:5], 1, s[64:65]
	v_or_b32_e32 v2, 4, v0
	v_mov_b32_e32 v3, v1
	v_lshlrev_b64 v[4:5], 9, v[2:3]
	v_or_b32_e32 v4, v4, v12
	v_or_b32_e32 v4, s84, v4
	v_lshlrev_b64 v[2:3], 11, v[2:3]
	v_lshl_add_u64 v[6:7], v[4:5], 2, s[60:61]
	v_lshl_add_u64 v[64:65], v[72:73], 0, v[2:3]
	v_lshl_add_u64 v[2:3], v[4:5], 1, s[64:65]
	v_or_b32_e32 v2, 5, v0
	v_mov_b32_e32 v3, v1
	v_lshlrev_b64 v[4:5], 9, v[2:3]
	v_or_b32_e32 v4, v4, v12
	v_or_b32_e32 v4, s84, v4
	v_lshlrev_b64 v[2:3], 11, v[2:3]
	v_lshl_add_u64 v[6:7], v[4:5], 2, s[60:61]
	v_lshl_add_u64 v[58:59], v[72:73], 0, v[2:3]
	v_lshl_add_u64 v[2:3], v[4:5], 1, s[64:65]
	v_or_b32_e32 v2, 6, v0
	v_mov_b32_e32 v3, v1
	v_lshlrev_b64 v[4:5], 9, v[2:3]
	v_or_b32_e32 v4, v4, v12
	v_or_b32_e32 v4, s84, v4
	v_lshlrev_b64 v[2:3], 11, v[2:3]
	v_lshl_add_u64 v[6:7], v[4:5], 2, s[60:61]
	v_lshl_add_u64 v[60:61], v[72:73], 0, v[2:3]
	v_lshl_add_u64 v[2:3], v[4:5], 1, s[64:65]
	v_or_b32_e32 v2, 7, v0
	v_mov_b32_e32 v3, v1
	v_lshlrev_b64 v[4:5], 9, v[2:3]
	v_or_b32_e32 v4, v4, v12
	v_or_b32_e32 v4, s84, v4
	v_lshlrev_b64 v[2:3], 11, v[2:3]
	v_lshl_add_u64 v[6:7], v[4:5], 2, s[60:61]
	v_lshl_add_u64 v[54:55], v[72:73], 0, v[2:3]
	v_lshl_add_u64 v[2:3], v[4:5], 1, s[64:65]
	v_or_b32_e32 v2, 8, v0
	v_mov_b32_e32 v3, v1
	v_lshlrev_b64 v[4:5], 9, v[2:3]
	v_or_b32_e32 v4, v4, v12
	v_or_b32_e32 v4, s84, v4
	v_lshlrev_b64 v[2:3], 11, v[2:3]
	v_lshl_add_u64 v[6:7], v[4:5], 2, s[60:61]
	v_lshl_add_u64 v[56:57], v[72:73], 0, v[2:3]
	v_lshl_add_u64 v[2:3], v[4:5], 1, s[64:65]
	v_or_b32_e32 v2, 9, v0
	v_mov_b32_e32 v3, v1
	v_lshlrev_b64 v[4:5], 9, v[2:3]
	v_or_b32_e32 v4, v4, v12
	v_or_b32_e32 v4, s84, v4
	v_lshlrev_b64 v[2:3], 11, v[2:3]
	v_lshl_add_u64 v[6:7], v[4:5], 2, s[60:61]
	v_lshl_add_u64 v[50:51], v[72:73], 0, v[2:3]
	v_lshl_add_u64 v[2:3], v[4:5], 1, s[64:65]
	v_or_b32_e32 v2, 10, v0
	v_mov_b32_e32 v3, v1
	v_lshlrev_b64 v[4:5], 9, v[2:3]
	v_or_b32_e32 v4, v4, v12
	v_or_b32_e32 v4, s84, v4
	v_lshlrev_b64 v[2:3], 11, v[2:3]
	v_lshl_add_u64 v[6:7], v[4:5], 2, s[60:61]
	v_lshl_add_u64 v[52:53], v[72:73], 0, v[2:3]
	v_lshl_add_u64 v[2:3], v[4:5], 1, s[64:65]
	v_or_b32_e32 v2, 11, v0
	v_mov_b32_e32 v3, v1
	v_lshlrev_b64 v[4:5], 9, v[2:3]
	v_or_b32_e32 v4, v4, v12
	v_or_b32_e32 v4, s84, v4
	v_lshl_add_u64 v[6:7], v[4:5], 2, s[60:61]
	v_lshlrev_b64 v[2:3], 11, v[2:3]
	v_lshl_add_u64 v[6:7], v[72:73], 0, v[2:3]
	v_lshl_add_u64 v[2:3], v[4:5], 1, s[64:65]
	v_or_b32_e32 v2, 12, v0
	v_mov_b32_e32 v3, v1
	v_lshlrev_b64 v[4:5], 9, v[2:3]
	v_or_b32_e32 v4, v4, v12
	v_or_b32_e32 v4, s84, v4
	v_lshl_add_u64 v[48:49], v[4:5], 2, s[60:61]
	v_lshlrev_b64 v[2:3], 11, v[2:3]
	v_lshl_add_u64 v[48:49], v[72:73], 0, v[2:3]
	v_lshl_add_u64 v[2:3], v[4:5], 1, s[64:65]
	v_or_b32_e32 v2, 13, v0
	v_mov_b32_e32 v3, v1
	v_lshlrev_b64 v[4:5], 9, v[2:3]
	v_or_b32_e32 v4, v4, v12
	v_or_b32_e32 v4, s84, v4
	v_lshl_add_u64 v[96:97], v[4:5], 2, s[60:61]
	v_lshl_add_u64 v[4:5], v[4:5], 1, s[64:65]
	v_or_b32_e32 v4, 14, v0
	v_mov_b32_e32 v5, v1
	v_lshlrev_b64 v[96:97], 9, v[4:5]
	v_or_b32_e32 v33, v96, v12
	v_or_b32_e32 v96, s84, v33
	v_lshl_add_u64 v[98:99], v[96:97], 2, s[60:61]
	v_lshl_add_u64 v[96:97], v[96:97], 1, s[64:65]
	v_or_b32_e32 v0, 15, v0
	v_lshlrev_b64 v[96:97], 9, v[0:1]
	v_or_b32_e32 v33, v96, v12
	v_lshlrev_b64 v[2:3], 11, v[2:3]
	v_lshlrev_b64 v[4:5], 11, v[4:5]
	v_or_b32_e32 v96, s84, v33
	v_lshlrev_b64 v[0:1], 11, v[0:1]
	v_lshl_add_u64 v[2:3], v[72:73], 0, v[2:3]
	v_lshl_add_u64 v[4:5], v[72:73], 0, v[4:5]
	v_lshl_add_u64 v[0:1], v[72:73], 0, v[0:1]
	v_lshl_add_u64 v[72:73], v[96:97], 1, s[64:65]
	s_mov_b32 s2, 0x5040100
	v_lshl_add_u64 v[98:99], v[96:97], 2, s[60:61]
	s_waitcnt vmcnt(0) lgkmcnt(0)
; #define LAS __attribute__((address_space(3)))
; __device__ __forceinline__ float bf2f(unsigned short h) { return __uint_as_float(((unsigned)h) << 16); }
; __device__ __forceinline__ unsigned short f2bf(float f) { return (unsigned short)(cvt_pk_bf16(f, 0.f) & 0xffffu); }
; __device__ __forceinline__ void hgrn_pass1_unit(Frame& F, int unit) {
;     ...
;     for (int i = 0; i < 16; ++i) { const size_t r = row0 + 16 * tq + i; lf[i] = LF[r * 512 + h * 128 + k]; qv[i] = QO[r * DM + h * 128 + k]; vv[i] = VH[r * 512 + h * 128 + k]; }
;     float run = 0.f;
; #pragma unroll
;     for (int i = 0; i < 16; ++i) { run += lf[i]; g[i] = run; }
;     tot[tq * 128 + k] = run;
;     { v4u w0, w1; w0.x = vv[0] | (vv[1] << 16); w0.y = vv[2] | (vv[3] << 16); w0.z = vv[4] | (vv[5] << 16); w0.w = vv[6] | (vv[7] << 16); w1.x = vv[8] | (vv[9] << 16); w1.y = vv[10] | (vv[11] << 16); w1.z = vv[12] | (vv[13] << 16); w1.w = vv[14] | (vv[15] << 16);
;       *(LAS v4u*)(VT + k * HG_LDS + 16 * tq) = w0; *(LAS v4u*)(VT + k * HG_LDS + 16 * tq + 8) = w1; }
;     __syncthreads();
;     const float t0 = tot[k], t1 = tot[128 + k], t2 = tot[256 + k], t3 = tot[384 + k];
;     const float off = (tq > 0 ? t0 : 0.f) + (tq > 1 ? t1 : 0.f) + (tq > 2 ? t2 : 0.f), gmid = t0 + t1, glast = gmid + t2 + t3;
;     float kl[16];
; #pragma unroll
;     for (int i = 0; i < 16; ++i) { const size_t r = row0 + 16 * tq + i; const float gi = off + g[i], q = bf2f(qv[i]), kk = 1.f - __expf(lf[i]);
;         QO[r * DM + h * 128 + k] = f2bf(q * __expf(gi));
;         Qm[(16 * tq + i) * HG_LDK + k] = f2bf(q * __expf(fminf(gi - gmid, 80.f)));
;         Km[(16 * tq + i) * HG_LDK + k] = f2bf(kk * __expf(fminf(gmid - gi, 80.f)));
;         kl[i] = kk * __expf(glast - gi); }
	v_mov_b32_e32 v95, v226
	v_mov_b32_e32 v74, v172
	v_mov_b32_e32 v93, v179
	v_mov_b32_e32 v75, v173
	v_mov_b32_e32 v92, v178
	v_mov_b32_e32 v76, v174
	v_mov_b32_e32 v91, v225
	v_mov_b32_e32 v77, v175
	v_mov_b32_e32 v89, v177
	v_mov_b32_e32 v101, v185
	v_mov_b32_e32 v88, v176
	v_mov_b32_e32 v104, v228
	v_mov_b32_e32 v86, v224
	v_mov_b32_e32 v107, v187
	v_mov_b32_e32 v85, v223
	v_mov_b32_e32 v108, v188
	v_mov_b32_e32 v83, v222
	v_mov_b32_e32 v110, v229
	v_mov_b32_e32 v47, v221
	v_mov_b32_e32 v112, v190
	v_mov_b32_e32 v45, v220
	v_mov_b32_e32 v115, v230
	v_mov_b32_e32 v41, v219
	v_mov_b32_e32 v117, v195
	v_mov_b32_e32 v39, v218
	v_mov_b32_e32 v120, v232
	v_mov_b32_e32 v37, v214
	v_mov_b32_e32 v126, v204
	v_mov_b32_e32 v127, v205
	v_mov_b32_e32 v35, v202
	v_mov_b32_e32 v72, v170
	v_mov_b32_e32 v33, v137
	v_mov_b32_e32 v129, v233
	v_mov_b32_e32 v130, v206
	v_mov_b32_e32 v131, v207
	v_mov_b32_e32 v132, v208
	v_mov_b32_e32 v133, v209
	v_mov_b32_e32 v134, v210
	v_mov_b32_e32 v135, v211
	v_mov_b32_e32 v136, v234
	v_mov_b32_e32 v119, v231
	v_mov_b32_e32 v116, v194
	v_mov_b32_e32 v113, v191
	v_mov_b32_e32 v109, v189
	v_mov_b32_e32 v106, v186
	v_mov_b32_e32 v103, v227
	v_mov_b32_e32 v100, v184
	v_mov_b32_e32 v98, v182
	v_add_f32_e32 v73, 0, v95
	v_add_f32_e32 v128, v73, v93
	v_add_f32_e32 v121, v128, v92
	v_add_f32_e32 v118, v121, v91
	v_add_f32_e32 v114, v118, v89
	v_add_f32_e32 v111, v114, v88
	v_add_f32_e32 v105, v111, v86
	v_add_f32_e32 v102, v105, v85
	v_add_f32_e32 v99, v102, v83
	v_perm_b32 v125, v108, v107, s2
	v_perm_b32 v124, v104, v101, s2
	v_add_f32_e32 v97, v99, v47
	v_perm_b32 v123, v77, v76, s2
	v_perm_b32 v122, v75, v74, s2
	v_perm_b32 v74, v112, v110, s2
	v_mul_f32_e32 v47, 0x3fb8aa3b, v47
	s_ashr_i32 s45, s44, 31
	v_add_f32_e32 v96, v97, v45
	v_mul_f32_e32 v45, 0x3fb8aa3b, v45
	v_add_f32_e32 v94, v96, v41
	v_mul_f32_e32 v41, 0x3fb8aa3b, v41
	v_perm_b32 v75, v117, v115, s2
	v_add_f32_e32 v90, v94, v39
	v_add_f32_e32 v87, v90, v37
	v_perm_b32 v76, v126, v120, s2
	v_add_f32_e32 v84, v87, v35
	v_perm_b32 v77, v72, v127, s2
	v_add_f32_e32 v43, v84, v33
	ds_write_b32 v9, v43
	ds_write_b128 v13, v[122:125] offset:53248
	ds_write_b128 v13, v[74:77] offset:53264
	s_waitcnt lgkmcnt(0)
	s_barrier
	ds_read2st64_b32 v[74:75], v15 offset1:2
	ds_read2st64_b32 v[122:123], v15 offset0:4 offset1:6
	s_waitcnt lgkmcnt(1)
	v_cndmask_b32_e64 v77, 0, v74, s[18:19]
	v_cndmask_b32_e64 v125, 0, v75, s[20:21]
	v_mov_b32_e32 v76, v74
	v_mov_b32_e32 v124, v75
	s_waitcnt lgkmcnt(0)
	v_cndmask_b32_e64 v127, 0, v122, s[22:23]
	v_pk_add_f32 v[74:75], v[76:77], v[124:125]
	v_mov_b32_e32 v126, v122
	v_pk_add_f32 v[76:77], v[74:75], v[126:127]
	v_mov_b32_e32 v72, v123
	v_pk_add_f32 v[72:73], v[76:77], v[72:73]
	v_mul_f32_e32 v76, 0x3fb8aa3b, v95
	v_exp_f32_e32 v122, v76
	v_mul_f32_e32 v76, 0x3fb8aa3b, v73
	v_exp_f32_e32 v76, v76
	v_lshlrev_b32_e32 v75, 16, v129
	v_mul_f32_e32 v76, v76, v75
	v_cvt_pk_bf16_f32 v76, v76, s0
	flat_store_short v[70:71], v76
	v_sub_f32_e32 v70, v73, v74
	v_min_f32_e32 v70, 0x42a00000, v70
	v_mul_f32_e32 v70, 0x3fb8aa3b, v70
	v_exp_f32_e32 v70, v70
	v_add_f32_e32 v71, v128, v77
	v_mul_f32_e32 v76, 0x3fb8aa3b, v93
	v_sub_f32_e32 v93, v71, v74
	v_mul_f32_e32 v70, v70, v75
	v_cvt_pk_bf16_f32 v70, v70, s0
	ds_write_b16 v23, v70
	v_sub_f32_e32 v70, v74, v73
	v_min_f32_e32 v70, 0x42a00000, v70
	v_mul_f32_e32 v70, 0x3fb8aa3b, v70
	v_exp_f32_e32 v123, v76
	v_mul_f32_e32 v76, 0x3fb8aa3b, v71
	v_min_f32_e32 v93, 0x42a00000, v93
	v_exp_f32_e32 v75, v70
	v_exp_f32_e32 v76, v76
	v_mul_f32_e32 v93, 0x3fb8aa3b, v93
	v_exp_f32_e32 v93, v93
	v_sub_f32_e32 v70, v72, v73
	v_lshlrev_b32_e32 v73, 16, v130
	v_pk_add_f32 v[122:123], v[122:123], 1.0 op_sel_hi:[1,0] neg_lo:[1,0] neg_hi:[1,0]
	v_mul_f32_e32 v76, v76, v73
	v_mul_f32_e32 v75, v122, v75
	v_cvt_pk_bf16_f32 v76, v76, s0
	v_mul_f32_e32 v73, v93, v73
	v_sub_f32_e32 v93, v74, v71
	v_cvt_pk_bf16_f32 v75, v75, s0
	v_min_f32_e32 v93, 0x42a00000, v93
	ds_write_b16 v23, v75 offset:17408
	flat_store_short v[66:67], v76
	v_add_f32_e32 v67, v121, v77
	v_mul_f32_e32 v93, 0x3fb8aa3b, v93
	v_mul_f32_e32 v75, 0x3fb8aa3b, v67
	v_exp_f32_e32 v93, v93
	v_exp_f32_e32 v75, v75
	v_cvt_pk_bf16_f32 v73, v73, s0
	ds_write_b16 v23, v73 offset:272
	v_lshlrev_b32_e32 v73, 16, v131
	v_mul_f32_e32 v66, v123, v93
	v_mul_f32_e32 v75, v75, v73
	v_cvt_pk_bf16_f32 v66, v66, s0
	v_cvt_pk_bf16_f32 v75, v75, s0
	ds_write_b16 v23, v66 offset:17680
	flat_store_short v[68:69], v75
	v_sub_f32_e32 v68, v67, v74
	v_min_f32_e32 v68, 0x42a00000, v68
	v_mul_f32_e32 v68, 0x3fb8aa3b, v68
	v_exp_f32_e32 v68, v68
	v_add_f32_e32 v69, v118, v77
	v_mul_f32_e32 v76, 0x3fb8aa3b, v69
	v_exp_f32_e32 v76, v76
	v_mul_f32_e32 v68, v68, v73
	v_cvt_pk_bf16_f32 v68, v68, s0
	ds_write_b16 v23, v68 offset:544
	v_sub_f32_e32 v68, v74, v67
	v_min_f32_e32 v68, 0x42a00000, v68
	v_sub_f32_e32 v67, v72, v67
	v_mul_f32_e32 v68, 0x3fb8aa3b, v68
	v_mul_f32_e32 v67, 0x3fb8aa3b, v67
	v_exp_f32_e32 v73, v68
	v_exp_f32_e32 v68, v67
	v_mul_f32_e32 v67, 0x3fb8aa3b, v91
	v_sub_f32_e32 v91, v69, v74
	v_min_f32_e32 v91, 0x42a00000, v91
	v_mul_f32_e32 v91, 0x3fb8aa3b, v91
	v_exp_f32_e32 v91, v91
	v_mul_f32_e32 v66, 0x3fb8aa3b, v92
	v_exp_f32_e32 v66, v66
	v_exp_f32_e32 v67, v67
	v_lshlrev_b32_e32 v75, 16, v132
	v_mul_f32_e32 v76, v76, v75
	v_mul_f32_e32 v75, v91, v75
	v_sub_f32_e32 v91, v74, v69
	v_sub_f32_e32 v69, v72, v69
	v_mul_f32_e32 v69, 0x3fb8aa3b, v69
	v_exp_f32_e32 v69, v69
	v_pk_add_f32 v[92:93], v[66:67], 1.0 op_sel_hi:[1,0] neg_lo:[1,0] neg_hi:[1,0]
	v_cvt_pk_bf16_f32 v76, v76, s0
	v_mul_f32_e32 v66, v92, v73
	v_cvt_pk_bf16_f32 v66, v66, s0
	v_min_f32_e32 v91, 0x42a00000, v91
; __device__ __forceinline__ float bf2f(unsigned short h) { return __uint_as_float(((unsigned)h) << 16); }
; __device__ __forceinline__ unsigned short f2bf(float f) { return (unsigned short)(cvt_pk_bf16(f, 0.f) & 0xffffu); }
; __device__ __forceinline__ void hgrn_pass1_unit(Frame& F, int unit) {
;     ...
;     for (int i = 0; i < 16; ++i) { const size_t r = row0 + 16 * tq + i; const float gi = off + g[i], q = bf2f(qv[i]), kk = 1.f - __expf(lf[i]);
;         QO[r * DM + h * 128 + k] = f2bf(q * __expf(gi));
;         Qm[(16 * tq + i) * HG_LDK + k] = f2bf(q * __expf(fminf(gi - gmid, 80.f)));
;         Km[(16 * tq + i) * HG_LDK + k] = f2bf(kk * __expf(fminf(gmid - gi, 80.f)));
;         kl[i] = kk * __expf(glast - gi); }
	ds_write_b16 v23, v66 offset:17952
	flat_store_short v[62:63], v76
	v_add_f32_e32 v63, v114, v77
	v_mul_f32_e32 v91, 0x3fb8aa3b, v91
	v_pk_mul_f32 v[66:67], v[92:93], v[68:69]
	v_mul_f32_e32 v69, 0x3fb8aa3b, v63
	v_exp_f32_e32 v91, v91
	v_exp_f32_e32 v69, v69
	v_lshlrev_b32_e32 v68, 16, v133
	v_cvt_pk_bf16_f32 v75, v75, s0
	v_mul_f32_e32 v62, v93, v91
	v_mul_f32_e32 v69, v69, v68
	v_cvt_pk_bf16_f32 v62, v62, s0
	v_cvt_pk_bf16_f32 v69, v69, s0
	ds_write_b16 v23, v75 offset:816
	ds_write_b16 v23, v62 offset:18224
	flat_store_short v[64:65], v69
	v_sub_f32_e32 v64, v63, v74
	v_min_f32_e32 v64, 0x42a00000, v64
	v_mul_f32_e32 v64, 0x3fb8aa3b, v64
	v_add_f32_e32 v65, v111, v77
	v_exp_f32_e32 v64, v64
	v_mul_f32_e32 v69, 0x3fb8aa3b, v65
	v_exp_f32_e32 v69, v69
	v_mul_f32_e32 v62, 0x3fb8aa3b, v89
	v_mul_f32_e32 v64, v64, v68
	v_lshlrev_b32_e32 v68, 16, v134
	v_mul_f32_e32 v69, v69, v68
	v_cvt_pk_bf16_f32 v75, v69, s0
	v_sub_f32_e32 v69, v65, v74
	v_min_f32_e32 v69, 0x42a00000, v69
	v_cvt_pk_bf16_f32 v64, v64, s0
	v_mul_f32_e32 v69, 0x3fb8aa3b, v69
	ds_write_b16 v23, v64 offset:1088
	v_sub_f32_e32 v64, v74, v63
	v_exp_f32_e32 v69, v69
	v_min_f32_e32 v64, 0x42a00000, v64
	v_sub_f32_e32 v63, v72, v63
	v_mul_f32_e32 v64, 0x3fb8aa3b, v64
	v_mul_f32_e32 v63, 0x3fb8aa3b, v63
	v_exp_f32_e32 v73, v64
	v_exp_f32_e32 v64, v63
	v_mul_f32_e32 v63, 0x3fb8aa3b, v88
	v_exp_f32_e32 v62, v62
	v_exp_f32_e32 v63, v63
	v_mul_f32_e32 v68, v69, v68
	v_cvt_pk_bf16_f32 v76, v68, s0
	v_sub_f32_e32 v68, v74, v65
	v_min_f32_e32 v68, 0x42a00000, v68
	v_sub_f32_e32 v65, v72, v65
	v_mul_f32_e32 v68, 0x3fb8aa3b, v68
	v_mul_f32_e32 v65, 0x3fb8aa3b, v65
	v_exp_f32_e32 v88, v68
	v_exp_f32_e32 v65, v65
	v_pk_add_f32 v[68:69], v[62:63], 1.0 op_sel_hi:[1,0] neg_lo:[1,0] neg_hi:[1,0]
	v_sub_f32_e32 v71, v72, v71
	v_mul_f32_e32 v62, v68, v73
	v_cvt_pk_bf16_f32 v62, v62, s0
	ds_write_b16 v23, v62 offset:18496
	flat_store_short v[58:59], v75
	v_add_f32_e32 v59, v105, v77
	v_pk_mul_f32 v[62:63], v[68:69], v[64:65]
	v_mul_f32_e32 v65, 0x3fb8aa3b, v59
	v_exp_f32_e32 v65, v65
	v_lshlrev_b32_e32 v64, 16, v135
	v_mul_f32_e32 v58, v69, v88
	v_cvt_pk_bf16_f32 v58, v58, s0
	v_mul_f32_e32 v65, v65, v64
	v_cvt_pk_bf16_f32 v65, v65, s0
	ds_write_b16 v23, v76 offset:1360
	ds_write_b16 v23, v58 offset:18768
	flat_store_short v[60:61], v65
	v_sub_f32_e32 v60, v59, v74
	v_min_f32_e32 v60, 0x42a00000, v60
	v_mul_f32_e32 v60, 0x3fb8aa3b, v60
	v_add_f32_e32 v61, v102, v77
	v_exp_f32_e32 v60, v60
	v_mul_f32_e32 v65, 0x3fb8aa3b, v61
	v_exp_f32_e32 v65, v65
	v_mul_f32_e32 v58, 0x3fb8aa3b, v86
	v_mul_f32_e32 v60, v60, v64
	v_lshlrev_b32_e32 v64, 16, v136
	v_mul_f32_e32 v65, v65, v64
	v_cvt_pk_bf16_f32 v69, v65, s0
	v_sub_f32_e32 v65, v61, v74
	v_min_f32_e32 v65, 0x42a00000, v65
	v_cvt_pk_bf16_f32 v60, v60, s0
	v_mul_f32_e32 v65, 0x3fb8aa3b, v65
	ds_write_b16 v23, v60 offset:1632
	v_sub_f32_e32 v60, v74, v59
	v_exp_f32_e32 v65, v65
	v_min_f32_e32 v60, 0x42a00000, v60
	v_sub_f32_e32 v59, v72, v59
	v_mul_f32_e32 v60, 0x3fb8aa3b, v60
	v_mul_f32_e32 v59, 0x3fb8aa3b, v59
	v_exp_f32_e32 v68, v60
	v_exp_f32_e32 v60, v59
	v_mul_f32_e32 v59, 0x3fb8aa3b, v85
	v_exp_f32_e32 v58, v58
	v_exp_f32_e32 v59, v59
	v_mul_f32_e32 v64, v65, v64
	v_cvt_pk_bf16_f32 v73, v64, s0
	v_sub_f32_e32 v64, v74, v61
	v_min_f32_e32 v64, 0x42a00000, v64
	v_sub_f32_e32 v61, v72, v61
	v_mul_f32_e32 v64, 0x3fb8aa3b, v64
	v_mul_f32_e32 v61, 0x3fb8aa3b, v61
	v_exp_f32_e32 v75, v64
	v_exp_f32_e32 v61, v61
	v_pk_add_f32 v[64:65], v[58:59], 1.0 op_sel_hi:[1,0] neg_lo:[1,0] neg_hi:[1,0]
	v_mul_f32_e32 v70, 0x3fb8aa3b, v70
	v_mul_f32_e32 v58, v64, v68
	v_cvt_pk_bf16_f32 v58, v58, s0
	ds_write_b16 v23, v58 offset:19040
	flat_store_short v[54:55], v69
	v_add_f32_e32 v55, v99, v77
	v_pk_mul_f32 v[58:59], v[64:65], v[60:61]
	v_mul_f32_e32 v61, 0x3fb8aa3b, v55
	v_exp_f32_e32 v61, v61
	v_lshlrev_b32_e32 v60, 16, v119
	v_mul_f32_e32 v54, v65, v75
	v_cvt_pk_bf16_f32 v54, v54, s0
	v_mul_f32_e32 v61, v61, v60
	v_cvt_pk_bf16_f32 v61, v61, s0
	ds_write_b16 v23, v73 offset:1904
	ds_write_b16 v23, v54 offset:19312
	flat_store_short v[56:57], v61
	v_sub_f32_e32 v56, v55, v74
	v_min_f32_e32 v56, 0x42a00000, v56
	v_mul_f32_e32 v56, 0x3fb8aa3b, v56
	v_exp_f32_e32 v56, v56
	v_add_f32_e32 v57, v97, v77
	v_sub_f32_e32 v61, v57, v74
	v_min_f32_e32 v61, 0x42a00000, v61
	v_mul_f32_e32 v56, v56, v60
	v_cvt_pk_bf16_f32 v56, v56, s0
	ds_write_b16 v23, v56 offset:2176
	v_sub_f32_e32 v56, v74, v55
	v_min_f32_e32 v56, 0x42a00000, v56
	v_sub_f32_e32 v55, v72, v55
	v_mul_f32_e32 v56, 0x3fb8aa3b, v56
	v_mul_f32_e32 v55, 0x3fb8aa3b, v55
	v_exp_f32_e32 v64, v56
	v_exp_f32_e32 v56, v55
	v_exp_f32_e32 v55, v47
	v_mul_f32_e32 v47, 0x3fb8aa3b, v57
	v_mul_f32_e32 v61, 0x3fb8aa3b, v61
	v_exp_f32_e32 v47, v47
	v_exp_f32_e32 v61, v61
	v_lshlrev_b32_e32 v60, 16, v116
	v_mul_f32_e32 v54, 0x3fb8aa3b, v83
	v_mul_f32_e32 v47, v47, v60
	v_mul_f32_e32 v60, v61, v60
	v_exp_f32_e32 v54, v54
	v_cvt_pk_bf16_f32 v65, v60, s0
	v_sub_f32_e32 v60, v74, v57
	v_min_f32_e32 v60, 0x42a00000, v60
	v_mul_f32_e32 v60, 0x3fb8aa3b, v60
	v_exp_f32_e32 v68, v60
	v_pk_add_f32 v[60:61], v[54:55], 1.0 op_sel_hi:[1,0] neg_lo:[1,0] neg_hi:[1,0]
	v_cvt_pk_bf16_f32 v47, v47, s0
	v_mul_f32_e32 v54, v60, v64
	v_cvt_pk_bf16_f32 v54, v54, s0
	ds_write_b16 v23, v54 offset:19584
	flat_store_short v[50:51], v47
	v_mul_f32_e32 v47, v61, v68
	v_cvt_pk_bf16_f32 v47, v47, s0
	ds_write_b16 v23, v47 offset:19856
	v_add_f32_e32 v47, v96, v77
	v_exp_f32_e32 v50, v45
	v_mul_f32_e32 v45, 0x3fb8aa3b, v47
	v_exp_f32_e32 v45, v45
	v_lshlrev_b32_e32 v51, 16, v113
	ds_write_b16 v23, v65 offset:2448
	v_sub_f32_e32 v57, v72, v57
	v_mul_f32_e32 v45, v45, v51
; __device__ __forceinline__ unsigned cvt_pk_bf16(float lo, float hi) { const f32x2cv v = {lo, hi}; const bf16x2cv b = __builtin_convertvector(v, bf16x2cv); return __builtin_bit_cast(unsigned, b); }
; #define LAS __attribute__((address_space(3)))
; __device__ __forceinline__ float bf2f(unsigned short h) { return __uint_as_float(((unsigned)h) << 16); }
; __device__ __forceinline__ unsigned short f2bf(float f) { return (unsigned short)(cvt_pk_bf16(f, 0.f) & 0xffffu); }
; __device__ __forceinline__ void hgrn_pass1_unit(Frame& F, int unit) {
;     ...
;     for (int i = 0; i < 16; ++i) { const size_t r = row0 + 16 * tq + i; const float gi = off + g[i], q = bf2f(qv[i]), kk = 1.f - __expf(lf[i]);
;         QO[r * DM + h * 128 + k] = f2bf(q * __expf(gi));
;         Qm[(16 * tq + i) * HG_LDK + k] = f2bf(q * __expf(fminf(gi - gmid, 80.f)));
;         Km[(16 * tq + i) * HG_LDK + k] = f2bf(kk * __expf(fminf(gmid - gi, 80.f)));
;         kl[i] = kk * __expf(glast - gi); }
;     { v4u w0, w1; w0.x = cvt_pk_bf16(kl[0], kl[1]); w0.y = cvt_pk_bf16(kl[2], kl[3]); w0.z = cvt_pk_bf16(kl[4], kl[5]); w0.w = cvt_pk_bf16(kl[6], kl[7]); w1.x = cvt_pk_bf16(kl[8], kl[9]); w1.y = cvt_pk_bf16(kl[10], kl[11]); w1.z = cvt_pk_bf16(kl[12], kl[13]); w1.w = cvt_pk_bf16(kl[14], kl[15]);
;       *(LAS v4u*)(KlT + k * HG_LDS + 16 * tq) = w0; *(LAS v4u*)(KlT + k * HG_LDS + 16 * tq + 8) = w1; }
;     if (tq == 0) HD[k] = __expf(glast);
	v_cvt_pk_bf16_f32 v45, v45, s0
	flat_store_short v[52:53], v45
	v_sub_f32_e32 v45, v47, v74
	v_min_f32_e32 v45, 0x42a00000, v45
	v_mul_f32_e32 v45, 0x3fb8aa3b, v45
	v_exp_f32_e32 v45, v45
	v_mul_f32_e32 v57, 0x3fb8aa3b, v57
	v_exp_f32_e32 v57, v57
	v_lshlrev_b32_e32 v53, 16, v109
	v_mul_f32_e32 v45, v45, v51
	v_cvt_pk_bf16_f32 v45, v45, s0
	ds_write_b16 v23, v45 offset:2720
	v_sub_f32_e32 v45, v74, v47
	v_sub_f32_e32 v47, v72, v47
	v_mul_f32_e32 v47, 0x3fb8aa3b, v47
	v_exp_f32_e32 v52, v47
	v_add_f32_e32 v47, v94, v77
	v_pk_mul_f32 v[54:55], v[60:61], v[56:57]
	v_sub_f32_e32 v56, v47, v74
	v_min_f32_e32 v56, 0x42a00000, v56
	v_exp_f32_e32 v51, v41
	v_mul_f32_e32 v41, 0x3fb8aa3b, v47
	v_mul_f32_e32 v56, 0x3fb8aa3b, v56
	v_exp_f32_e32 v41, v41
	v_exp_f32_e32 v56, v56
	v_min_f32_e32 v45, 0x42a00000, v45
	v_mul_f32_e32 v45, 0x3fb8aa3b, v45
	v_mul_f32_e32 v41, v41, v53
	v_mul_f32_e32 v53, v56, v53
	v_cvt_pk_bf16_f32 v56, v53, s0
	v_sub_f32_e32 v53, v74, v47
	v_exp_f32_e32 v45, v45
	v_min_f32_e32 v53, 0x42a00000, v53
	v_mul_f32_e32 v53, 0x3fb8aa3b, v53
	v_exp_f32_e32 v57, v53
	v_pk_add_f32 v[50:51], v[50:51], 1.0 op_sel_hi:[1,0] neg_lo:[1,0] neg_hi:[1,0]
	v_cvt_pk_bf16_f32 v41, v41, s0
	v_mul_f32_e32 v45, v50, v45
	v_cvt_pk_bf16_f32 v45, v45, s0
	ds_write_b16 v23, v45 offset:20128
	flat_store_short v[6:7], v41
	v_mul_f32_e32 v6, v51, v57
	v_cvt_pk_bf16_f32 v6, v6, s0
	v_add_f32_e32 v7, v90, v77
	ds_write_b16 v23, v6 offset:20400
	v_mul_f32_e32 v6, 0x3fb8aa3b, v39
	v_mul_f32_e32 v39, 0x3fb8aa3b, v7
	v_exp_f32_e32 v39, v39
	v_lshlrev_b32_e32 v41, 16, v106
	ds_write_b16 v23, v56 offset:2992
	v_sub_f32_e32 v47, v72, v47
	v_mul_f32_e32 v39, v39, v41
	v_cvt_pk_bf16_f32 v39, v39, s0
	flat_store_short v[48:49], v39
	v_sub_f32_e32 v39, v7, v74
	v_min_f32_e32 v39, 0x42a00000, v39
	v_mul_f32_e32 v39, 0x3fb8aa3b, v39
	v_exp_f32_e32 v39, v39
	v_mul_f32_e32 v47, 0x3fb8aa3b, v47
	v_exp_f32_e32 v53, v47
	v_exp_f32_e32 v6, v6
	v_mul_f32_e32 v39, v39, v41
	v_cvt_pk_bf16_f32 v39, v39, s0
	v_add_f32_e32 v41, v87, v77
	ds_write_b16 v23, v39 offset:3264
	v_sub_f32_e32 v39, v74, v7
	v_sub_f32_e32 v7, v72, v7
	v_sub_f32_e32 v47, v41, v74
	v_mul_f32_e32 v7, 0x3fb8aa3b, v7
	v_min_f32_e32 v47, 0x42a00000, v47
	v_exp_f32_e32 v48, v7
	v_mul_f32_e32 v7, 0x3fb8aa3b, v37
	v_mul_f32_e32 v37, 0x3fb8aa3b, v41
	v_mul_f32_e32 v47, 0x3fb8aa3b, v47
	v_exp_f32_e32 v37, v37
	v_exp_f32_e32 v47, v47
	v_min_f32_e32 v39, 0x42a00000, v39
	v_mul_f32_e32 v39, 0x3fb8aa3b, v39
	v_lshlrev_b32_e32 v45, 16, v103
	v_exp_f32_e32 v7, v7
	v_exp_f32_e32 v39, v39
	v_mul_f32_e32 v37, v37, v45
	v_mul_f32_e32 v45, v47, v45
	v_sub_f32_e32 v47, v74, v41
	v_min_f32_e32 v47, 0x42a00000, v47
	v_sub_f32_e32 v41, v72, v41
	v_mul_f32_e32 v47, 0x3fb8aa3b, v47
	v_mul_f32_e32 v41, 0x3fb8aa3b, v41
	v_exp_f32_e32 v47, v47
	v_exp_f32_e32 v49, v41
	v_pk_add_f32 v[6:7], v[6:7], 1.0 op_sel_hi:[1,0] neg_lo:[1,0] neg_hi:[1,0]
	v_cvt_pk_bf16_f32 v37, v37, s0
	v_mul_f32_e32 v39, v6, v39
	v_cvt_pk_bf16_f32 v39, v39, s0
	ds_write_b16 v23, v39 offset:20672
	flat_store_short v[2:3], v37
	v_add_f32_e32 v3, v84, v77
	v_pk_mul_f32 v[48:49], v[6:7], v[48:49]
	v_mul_f32_e32 v2, v7, v47
	v_mul_f32_e32 v7, 0x3fb8aa3b, v3
	v_exp_f32_e32 v7, v7
	v_lshlrev_b32_e32 v6, 16, v100
	v_cvt_pk_bf16_f32 v45, v45, s0
	v_cvt_pk_bf16_f32 v2, v2, s0
	v_mul_f32_e32 v7, v7, v6
	v_cvt_pk_bf16_f32 v7, v7, s0
	ds_write_b16 v23, v45 offset:3536
	ds_write_b16 v23, v2 offset:20944
	flat_store_short v[4:5], v7
	v_sub_f32_e32 v4, v3, v74
	v_min_f32_e32 v4, 0x42a00000, v4
	v_mul_f32_e32 v4, 0x3fb8aa3b, v4
	v_exp_f32_e32 v4, v4
	v_add_f32_e32 v5, v43, v77
	v_mul_f32_e32 v2, 0x3fb8aa3b, v35
	v_sub_f32_e32 v35, v5, v74
	v_mul_f32_e32 v4, v4, v6
	v_cvt_pk_bf16_f32 v4, v4, s0
	ds_write_b16 v23, v4 offset:3808
	v_sub_f32_e32 v4, v74, v3
	v_min_f32_e32 v4, 0x42a00000, v4
	v_sub_f32_e32 v3, v72, v3
	v_mul_f32_e32 v4, 0x3fb8aa3b, v4
	v_mul_f32_e32 v3, 0x3fb8aa3b, v3
	v_min_f32_e32 v35, 0x42a00000, v35
	v_exp_f32_e32 v6, v4
	v_exp_f32_e32 v4, v3
	v_mul_f32_e32 v3, 0x3fb8aa3b, v33
	v_mul_f32_e32 v33, 0x3fb8aa3b, v5
	v_mul_f32_e32 v35, 0x3fb8aa3b, v35
	v_exp_f32_e32 v33, v33
	v_exp_f32_e32 v35, v35
	v_lshlrev_b32_e32 v7, 16, v98
	v_exp_f32_e32 v2, v2
	v_exp_f32_e32 v3, v3
	v_mul_f32_e32 v33, v33, v7
	v_mul_f32_e32 v7, v35, v7
	v_sub_f32_e32 v35, v74, v5
	v_min_f32_e32 v35, 0x42a00000, v35
	v_mul_f32_e32 v35, 0x3fb8aa3b, v35
	v_mul_f32_e32 v71, 0x3fb8aa3b, v71
	v_exp_f32_e32 v35, v35
	v_sub_f32_e32 v5, v72, v5
	v_exp_f32_e32 v70, v70
	v_exp_f32_e32 v71, v71
	v_mul_f32_e32 v5, 0x3fb8aa3b, v5
	v_pk_add_f32 v[2:3], v[2:3], 1.0 op_sel_hi:[1,0] neg_lo:[1,0] neg_hi:[1,0]
	v_exp_f32_e32 v5, v5
	v_mul_f32_e32 v6, v2, v6
	v_cvt_pk_bf16_f32 v33, v33, s0
	v_cvt_pk_bf16_f32 v6, v6, s0
	ds_write_b16 v23, v6 offset:21216
	flat_store_short v[0:1], v33
	v_mul_f32_e32 v0, v3, v35
	v_pk_mul_f32 v[70:71], v[122:123], v[70:71]
	v_cvt_pk_bf16_f32 v0, v0, s0
	v_pk_mul_f32 v[52:53], v[50:51], v[52:53]
	v_cvt_pk_bf16_f32 v7, v7, s0
	v_pk_mul_f32 v[50:51], v[2:3], v[4:5]
	ds_write_b16 v23, v0 offset:21488
	v_cvt_pk_bf16_f32 v0, v70, v71
	v_cvt_pk_bf16_f32 v1, v66, v67
	v_cvt_pk_bf16_f32 v2, v62, v63
	v_cvt_pk_bf16_f32 v3, v58, v59
	ds_write_b16 v23, v7 offset:4080
	v_cvt_pk_bf16_f32 v4, v54, v55
	v_cvt_pk_bf16_f32 v5, v52, v53
	v_cvt_pk_bf16_f32 v6, v48, v49
	v_cvt_pk_bf16_f32 v7, v50, v51
	ds_write_b128 v13, v[0:3] offset:34816
	ds_write_b128 v13, v[4:7] offset:34832
	s_and_saveexec_b64 s[84:85], s[24:25]
	s_cbranch_execz .LBB0_528
	v_mul_f32_e32 v0, 0x3fb8aa3b, v72
	v_exp_f32_e32 v2, v0
	s_lshl_b64 s[92:93], s[44:45], 9
	v_lshl_add_u64 v[0:1], v[20:21], 0, s[92:93]
	flat_store_dword v[0:1], v2
